# GEMM tile header: tile_map division by the row-group size (always 8) as shift/mask, no other change
# speedup vs baseline: 1.0088x; 1.0088x over previous
; __device__ __forceinline__ void gemm_stream(int swave, const GemmJob& J, char* shm, int vb, int G) {
;     ...
;   auto decode = [&](int id, int& g, int& brow, int& bcol, const bf16_t*& pA, const bf16_t*& pA1, const bf16_t*& pB) {
;     int pm, pn; g = 0;
;     if (J.nb == 1) tile_map(id, J.nM, J.nN, pm, pn);
;     else { g = id / per; const int rem = id - g * per; pm = rem / J.nN; pn = rem - pm * J.nN; }
;     brow = pm * 256; bcol = pn * 256;
;     pA = J.A + (size_t)g * J.strideA + (size_t)brow * lda; pA1 = J.A1 + (size_t)g * J.strideA + (size_t)brow * lda1; pB = J.Bt + (size_t)g * J.strideB + (size_t)bcol * ldb;
.LBB0_726:
	s_add_i32 s19, s19, s67
	s_cmp_ge_i32 s19, s24
	s_cselect_b64 s[6:7], -1, 0
	s_and_b64 vcc, exec, s[6:7]
	s_mov_b32 s28, s5
	s_mov_b32 s56, s4
	s_cbranch_vccnz .LBB0_728
	s_ashr_i32 s10, s19, 31
	s_lshr_b32 s10, s10, 29
	s_add_i32 s10, s19, s10
	s_ashr_i32 s11, s10, 3
	s_and_b32 s10, s10, -8
	s_sub_i32 s10, s19, s10
	s_lshr_b32 s12, s10, 31
	s_or_b32 s12, s12, s25
	s_mul_i32 s10, s12, s10
	s_add_i32 s10, s10, s11
	s_abs_i32 s12, s10
	s_mul_hi_u32 s13, s12, s41
	s_mul_i32 s14, s13, s40
	s_ashr_i32 s11, s10, 31
	s_sub_i32 s12, s12, s14
	s_xor_b32 s11, s11, s35
	s_add_i32 s14, s13, 1
	s_sub_i32 s15, s12, s40
	s_cmp_ge_u32 s12, s40
	s_cselect_b32 s13, s14, s13
	s_cselect_b32 s12, s15, s12
	s_add_i32 s14, s13, 1
	s_cmp_ge_u32 s12, s40
	s_cselect_b32 s12, s14, s13
	s_xor_b32 s12, s12, s11
	s_sub_i32 s11, s12, s11
	s_lshl_b32 s12, s11, 3
	s_mul_i32 s11, s11, s34
	s_sub_i32 s10, s10, s11
	s_lshr_b32 s11, s10, 3
	s_and_b32 s10, s10, 7
	s_add_i32 s10, s10, s12
	s_lshl_b32 s28, s10, 8
	s_ashr_i32 s12, s28, 31
	s_lshl_b32 s56, s11, 8
	s_mul_i32 s10, s12, s38
	s_mul_hi_u32 s11, s28, s38
	s_add_i32 s11, s11, s10
	s_mul_i32 s10, s28, s38
	s_lshl_b64 s[10:11], s[10:11], 1
	v_readlane_b32 s14, v246, 0
	v_readlane_b32 s15, v246, 1
	s_add_u32 s10, s14, s10
	s_mul_i32 s12, s12, s37
	s_mul_hi_u32 s13, s28, s37
	s_addc_u32 s11, s15, s11
	s_add_i32 s13, s13, s12
	s_mul_i32 s12, s28, s37
	s_lshl_b64 s[12:13], s[12:13], 1
	v_readlane_b32 s14, v247, 55
	v_readlane_b32 s15, v247, 56
	s_add_u32 s12, s14, s12
	s_addc_u32 s13, s15, s13
	s_ashr_i32 s14, s56, 31
	s_mul_i32 s14, s14, s76
	s_mul_hi_u32 s15, s56, s76
	s_add_i32 s15, s15, s14
	s_mul_i32 s14, s56, s76
	s_lshl_b64 s[14:15], s[14:15], 1
	v_readlane_b32 s20, v246, 2
	v_readlane_b32 s21, v246, 3
	s_add_u32 s14, s20, s14
	s_addc_u32 s15, s21, s15
